# attention unit prologue: tile-1/2 K/V loads hoisted next to the tile-0 and Q loads (one cold round trip less per unit), on the prologue-batching stack
# baseline (speedup 1.0000x reference)
.LBB0_693:
	s_ashr_i32 s54, s71, 5
	s_ashr_i32 s55, s54, 31
	s_lshl_b32 s8, s71, 8
	s_lshl_b64 s[6:7], s[54:55], 13
	s_and_b32 s55, s8, 0x1f00
	s_or_b32 s6, s6, s55
	s_mulk_i32 s7, 0xc0
	s_mul_hi_u32 s8, s6, 0xc0
	s_add_i32 s8, s8, s7
	s_mulk_i32 s6, 0xc0
	s_add_u32 s6, s4, s6
	s_addc_u32 s7, s5, s8
	s_mul_i32 s9, s54, 0x18c000
	s_mul_hi_i32 s8, s54, 0x18c000
	s_add_u32 s36, s35, s9
	s_addc_u32 s8, s46, s8
	s_mul_i32 s11, s54, 0x108000
	s_mul_hi_i32 s9, s54, 0x108000
	s_add_u32 s40, s47, s11
	s_addc_u32 s9, s49, s9
	v_mov_b32_e32 v178, v0
	s_and_b32 s41, s9, 0xffff
	s_and_b32 s37, s8, 0xffff
	s_mov_b32 s8, s40
	s_mov_b32 s9, s41
	s_mov_b32 s11, s39
	v_lshlrev_b32_e32 v191, 4, v178
	v_lshlrev_b32_e32 v14, 3, v178
	v_add_u32_e32 v192, 0x2000, v14
	buffer_load_dwordx4 v[2:5], v191, s[8:11], 0 offen
	buffer_load_dwordx4 v[6:9], v191, s[36:39], 0 offen
	buffer_load_dwordx2 v[10:11], v192, s[36:39], 0 offen
	v_ashrrev_i32_e32 v181, 6, v178
	v_and_b32_e32 v180, 31, v178
	v_lshlrev_b32_e32 v179, 5, v181
	v_or_b32_e32 v15, v179, v180
	v_mov_b64_e32 v[12:13], s[6:7]
	v_mad_i64_i32 v[12:13], s[6:7], v15, s3, v[12:13]
	v_and_b32_e32 v154, 32, v178
	v_lshl_add_u64 v[12:13], v[12:13], 0, v[154:155]
	global_load_dwordx4 v[118:121], v[12:13], off offset:16
	global_load_dwordx4 v[114:117], v[12:13], off
	global_load_dwordx4 v[110:113], v[12:13], off offset:80
	global_load_dwordx4 v[106:109], v[12:13], off offset:64
	global_load_dwordx4 v[102:105], v[12:13], off offset:144
	global_load_dwordx4 v[98:101], v[12:13], off offset:128
	buffer_load_dwordx2 v[76:77], v192, s[36:39], s63 offen
	buffer_load_dwordx2 v[172:173], v192, s[36:39], s64 offen
	buffer_load_dwordx4 v[58:61], v191, s[36:39], s63 offen
	buffer_load_dwordx4 v[160:163], v191, s[36:39], s64 offen
	buffer_load_dwordx4 v[62:65], v191, s[8:11], s53 offen
	buffer_load_dwordx4 v[156:159], v191, s[8:11], s65 offen
	v_ashrrev_i32_e32 v15, 2, v178
	v_mul_hi_i32 v16, v178, s60
	v_ashrrev_i32_e32 v17, 1, v178
	v_bfe_u32 v182, v178, 5, 1
	v_lshlrev_b32_e32 v19, 6, v15
	v_lshrrev_b32_e32 v15, 2, v15
	v_lshrrev_b32_e32 v20, 31, v16
	v_ashrrev_i32_e32 v16, 1, v16
	v_add_u32_e32 v17, 0x200, v17
	v_lshrrev_b32_e32 v18, 2, v178
	v_lshlrev_b32_e32 v51, 1, v182
	v_xor_b32_e32 v15, v15, v178
	v_add_u32_e32 v16, v16, v20
	v_mul_hi_i32 v20, v17, s60
	v_bitop3_b32 v18, v51, v18, 3 bitop3:0x78
	v_lshlrev_b32_e32 v15, 4, v15
	v_mul_lo_u32 v21, v16, 12
	v_lshrrev_b32_e32 v23, 31, v20
	v_ashrrev_i32_e32 v20, 1, v20
	v_mul_lo_u32 v22, v16, s3
	v_lshrrev_b32_e32 v16, 2, v16
	v_lshlrev_b32_e32 v78, 4, v18
	v_and_or_b32 v15, v15, 48, v19
	v_sub_u32_e32 v18, v178, v21
	v_add_u32_e32 v19, v20, v23
	v_bitop3_b32 v16, v16, v18, 3 bitop3:0x6c
	v_mul_lo_u32 v18, v19, 12
	v_mul_lo_u32 v20, v19, s3
	v_lshrrev_b32_e32 v19, 2, v19
	v_add_u32_e32 v193, 0, v15
	v_lshl_add_u32 v15, v16, 4, v22
	v_sub_u32_e32 v16, v17, v18
	v_bitop3_b32 v16, v19, v16, 3 bitop3:0x6c
	v_add_u32_e32 v195, 0, v15
	v_lshl_add_u32 v15, v16, 4, v20
	v_bfe_u32 v50, v178, 2, 2
	v_and_or_b32 v12, v14, 8, v15
	v_add_u32_e32 v197, 0, v12
	s_waitcnt vmcnt(0)
	v_mul_u32_u24_e32 v52, 0xc0, v180
	v_or_b32_e32 v79, v78, v52
	v_add_u32_e32 v194, 0, v79
	v_and_b32_e32 v183, 0x3fffffc0, v178
	v_lshl_add_u32 v183, v183, 2, 0
	v_and_b32_e32 v154, 63, v178
	v_cmp_gt_u32_e64 s[6:7], 32, v154
	v_lshl_add_u32 v185, v180, 2, v183
	v_lshlrev_b32_e32 v184, 4, v182
	s_mov_b32 s72, 0xc000
	s_mov_b32 s73, 1
	v_mov_b32_e32 v188, 0
	s_waitcnt vmcnt(0)
	ds_write_b128 v193, v[2:5]
	ds_write_b128 v195, v[6:9] offset:16384
	ds_write_b64 v197, v[10:11] offset:16384
	v_bitop3_b32 v2, v51, v50, 1 bitop3:0x36
	v_lshlrev_b32_e32 v80, 4, v2
	v_or_b32_e32 v81, v80, v52
	v_add_u32_e32 v196, 0, v81
	s_waitcnt lgkmcnt(0)
	s_barrier
	ds_read_b128 v[6:9], v196 offset:16384
	ds_read_b128 v[2:5], v194 offset:16384
	ds_read_b128 v[10:13], v194 offset:22528
	ds_read_b128 v[14:17], v196 offset:22528
	s_waitcnt lgkmcnt(2)
	v_mfma_scale_f32_32x32x64_f8f6f4 v[34:49], v[2:9], v[114:121], 0, v1, v1 op_sel_hi:[0,0,0]
	v_bitop3_b32 v2, v51, v50, 4 bitop3:0x36
	v_lshl_add_u32 v2, v2, 4, v52
	v_add_u32_e32 v198, 0, v2
	v_bitop3_b32 v2, v51, v50, 5 bitop3:0x36
	v_lshl_add_u32 v2, v2, 4, v52
	v_add_u32_e32 v199, 0, v2
	s_waitcnt lgkmcnt(0)
	v_mfma_scale_f32_32x32x64_f8f6f4 v[18:33], v[10:17], v[114:121], 0, v1, v1 op_sel_hi:[0,0,0]
	ds_read_b128 v[6:9], v199 offset:16384
	ds_read_b128 v[2:5], v198 offset:16384
	ds_read_b128 v[10:13], v198 offset:22528
	ds_read_b128 v[14:17], v199 offset:22528
	s_waitcnt lgkmcnt(2)
	v_mfma_scale_f32_32x32x64_f8f6f4 v[34:49], v[2:9], v[106:113], v[34:49], v1, v1 op_sel_hi:[0,0,0]
	v_bitop3_b32 v3, v51, v50, 9 bitop3:0x36
	v_bitop3_b32 v2, v51, v50, 8 bitop3:0x36
	v_lshl_add_u32 v3, v3, 4, v52
	v_lshl_add_u32 v2, v2, 4, v52
	v_add_u32_e32 v200, 0, v3
	v_add_u32_e32 v201, 0, v2
	ds_read_b128 v[6:9], v200 offset:16384
	ds_read_b128 v[2:5], v201 offset:16384
	ds_read_b128 v[50:53], v201 offset:22528
	ds_read_b128 v[54:57], v200 offset:22528
	s_waitcnt vmcnt(3)
	s_mov_b32 s11, 0x8000
	s_waitcnt vmcnt(1)
	ds_write_b128 v193, v[62:65] offset:8192
	ds_write_b128 v195, v[58:61] offset:28672
	ds_write_b64 v197, v[76:77] offset:28672
	s_waitcnt lgkmcnt(7)
	v_mfma_scale_f32_32x32x64_f8f6f4 v[18:33], v[10:17], v[106:113], v[18:33], v1, v1 op_sel_hi:[0,0,0]
	s_waitcnt lgkmcnt(0)
	s_barrier
	v_mfma_scale_f32_32x32x64_f8f6f4 v[34:49], v[2:9], v[98:105], v[34:49], v1, v1 op_sel_hi:[0,0,0]
	v_mov_b64_e32 v[2:3], s[12:13]
	v_mov_b64_e32 v[16:17], s[26:27]
	v_mov_b64_e32 v[4:5], s[14:15]
	v_mov_b64_e32 v[6:7], s[16:17]
	v_mov_b64_e32 v[8:9], s[18:19]
	v_mov_b64_e32 v[10:11], s[20:21]
	v_mov_b64_e32 v[12:13], s[22:23]
	v_mov_b64_e32 v[14:15], s[24:25]
	v_mfma_scale_f32_32x32x64_f8f6f4 v[18:33], v[50:57], v[98:105], v[18:33], v1, v1 op_sel_hi:[0,0,0]
	s_nop 10
	v_max_f32_e32 v50, v35, v35
	v_max_f32_e32 v51, v34, v34
	v_max_f32_e32 v50, v51, v50
	v_max3_f32 v50, v50, v36, v37
	v_max3_f32 v50, v50, v38, v39
	v_max3_f32 v50, v50, v40, v41
	v_max3_f32 v50, v50, v42, v43
	v_max3_f32 v50, v50, v44, v45
	v_max3_f32 v50, v50, v46, v47
	v_max3_f32 v50, v50, v48, v49
	v_max3_f32 v50, v50, v18, v19
	v_max3_f32 v50, v50, v20, v21
	v_max3_f32 v50, v50, v22, v23
	v_max3_f32 v50, v50, v24, v25
	v_max3_f32 v50, v50, v26, v27
	v_max3_f32 v50, v50, v28, v29
	v_max3_f32 v50, v50, v30, v31
	v_max3_f32 v50, v50, v32, v33
	v_mov_b32_e32 v51, v50
	s_nop 1
	v_permlane32_swap_b32_e32 v50, v51
	v_max_f32_e32 v51, v51, v51
	v_max_f32_e32 v50, v50, v50
	v_max_f32_e32 v50, v50, v51
	v_add_f32_e32 v51, 0x7149f2ca, v50
	v_cmp_ge_f32_e32 vcc, s61, v51
	s_cmp_eq_u64 vcc, exec
	v_max_f32_e32 v50, 0xf149f2ca, v50
	s_cselect_b64 vcc, -1, 0
	v_sub_f32_e32 v52, 0xf149f2ca, v50
	v_cndmask_b32_e32 v128, v50, v176, vcc
	v_mul_f32_e32 v52, 0x3dd53b94, v52
	v_fma_f32 v50, v128, s62, 4.0
	v_exp_f32_e32 v52, v52
	v_mov_b32_e32 v51, v50
	v_fmamk_f32 v34, v34, 0x3dd53b94, v50
	v_fmamk_f32 v35, v35, 0x3dd53b94, v50
	v_fmamk_f32 v36, v36, 0x3dd53b94, v50
	v_fmamk_f32 v37, v37, 0x3dd53b94, v50
	v_fmamk_f32 v38, v38, 0x3dd53b94, v50
	v_fmamk_f32 v39, v39, 0x3dd53b94, v50
	v_fmamk_f32 v40, v40, 0x3dd53b94, v50
	v_fmamk_f32 v41, v41, 0x3dd53b94, v50
	v_fmamk_f32 v42, v42, 0x3dd53b94, v50
	v_fmamk_f32 v43, v43, 0x3dd53b94, v50
	v_fmamk_f32 v44, v44, 0x3dd53b94, v50
	v_fmamk_f32 v45, v45, 0x3dd53b94, v50
	v_fmamk_f32 v46, v46, 0x3dd53b94, v50
	v_fmamk_f32 v47, v47, 0x3dd53b94, v50
	v_fmamk_f32 v48, v48, 0x3dd53b94, v50
	v_fmac_f32_e32 v51, 0x3dd53b94, v49
	v_pk_fma_f32 v[122:123], v[20:21], s[52:53], v[50:51] op_sel_hi:[1,0,0]
	v_pk_fma_f32 v[124:125], v[18:19], s[52:53], v[50:51] op_sel_hi:[1,0,0]
	v_exp_f32_e32 v144, v34
	v_exp_f32_e32 v145, v35
	v_exp_f32_e32 v136, v36
	v_exp_f32_e32 v138, v37
	v_exp_f32_e32 v142, v38
	v_exp_f32_e32 v143, v39
	v_exp_f32_e32 v140, v40
	v_exp_f32_e32 v141, v41
	v_exp_f32_e32 v137, v42
	v_exp_f32_e32 v139, v43
	v_exp_f32_e32 v130, v44
	v_exp_f32_e32 v131, v45
	v_exp_f32_e32 v134, v46
	v_exp_f32_e32 v135, v47
	v_exp_f32_e32 v132, v48
	v_exp_f32_e32 v133, v51
	v_lshlrev_b32_e32 v18, 6, v180
	v_lshlrev_b32_e32 v20, 7, v180
	v_or_b32_e32 v19, v78, v18
	v_or_b32_e32 v18, v80, v18
	v_sub_u32_e32 v21, v79, v20
	v_sub_u32_e32 v20, v81, v20
	v_cndmask_b32_e64 v202, v52, 1.0, vcc
	v_pk_fma_f32 v[126:127], v[32:33], s[52:53], v[50:51] op_sel_hi:[1,0,0]
	v_pk_fma_f32 v[72:73], v[30:31], s[52:53], v[50:51] op_sel_hi:[1,0,0]
	v_pk_fma_f32 v[74:75], v[28:29], s[52:53], v[50:51] op_sel_hi:[1,0,0]
	v_pk_fma_f32 v[66:67], v[26:27], s[52:53], v[50:51] op_sel_hi:[1,0,0]
	v_pk_fma_f32 v[68:69], v[24:25], s[52:53], v[50:51] op_sel_hi:[1,0,0]
	v_pk_fma_f32 v[70:71], v[22:23], s[52:53], v[50:51] op_sel_hi:[1,0,0]
	v_add_u32_e32 v189, 0, v19
	v_add_u32_e32 v190, 0, v18
	v_add_u32_e32 v187, 0, v21
	v_add_u32_e32 v186, 0, v20
	v_mov_b64_e32 v[64:65], v[16:17]
	v_mov_b64_e32 v[48:49], v[16:17]
	v_mov_b64_e32 v[32:33], v[16:17]
	v_mov_b64_e32 v[62:63], v[14:15]
	v_mov_b64_e32 v[60:61], v[12:13]
	v_mov_b64_e32 v[58:59], v[10:11]
	v_mov_b64_e32 v[56:57], v[8:9]
	v_mov_b64_e32 v[54:55], v[6:7]
	v_mov_b64_e32 v[52:53], v[4:5]
	v_mov_b64_e32 v[50:51], v[2:3]
	v_mov_b64_e32 v[46:47], v[14:15]
	v_mov_b64_e32 v[44:45], v[12:13]
	v_mov_b64_e32 v[42:43], v[10:11]
	v_mov_b64_e32 v[40:41], v[8:9]
	v_mov_b64_e32 v[38:39], v[6:7]
	v_mov_b64_e32 v[36:37], v[4:5]
	v_mov_b64_e32 v[34:35], v[2:3]
	v_mov_b64_e32 v[30:31], v[14:15]
	v_mov_b64_e32 v[28:29], v[12:13]
	v_mov_b64_e32 v[26:27], v[10:11]
	v_mov_b64_e32 v[24:25], v[8:9]
	v_mov_b64_e32 v[22:23], v[6:7]
	v_mov_b64_e32 v[20:21], v[4:5]
	v_mov_b64_e32 v[18:19], v[2:3]
